# P2 sample pooling on WGs 0-7: window-sum rows loaded once (all in flight) + pool_sample copy loads batched; on top of sample-attention rewrite
# speedup vs baseline: 1.0719x; 1.0048x over previous
; __global__ void __launch_bounds__(512, 2) mega(Params p) {
;     ...
;         for (int it = gt; it < 32 * 128; it += NGT) { const int cq = it & 127, b = it >> 7; const int c = cq * 4, gi = c >> 7, w = 2 << gi;
;             const float* sp = p.in[2] + (size_t)b * 15 * 512 + c; const float* up = upool + (size_t)(NP + b * 4) * 512 + c;
;             for (int t = 0; t < 4; ++t) { f32x4 sum = (f32x4){0.f, 0.f, 0.f, 0.f};
;                 for (int s = 0; s < w; ++s) { const int e = 15 + t - s; sum += e >= 15 ? *(const f32x4*)(up + (size_t)(e - 15) * 512) : *(const f32x4*)(sp + (size_t)e * 512); }
;                 const f32x4 uv = *(const f32x4*)(up + (size_t)t * 512); const f32x4 dv = sum * (1.0f / (float)w) - uv;
;                 u32x2 o; o.x = pk2(dv[0], dv[1]); o.y = pk2(dv[2], dv[3]); *(u32x2*)(dbuf + (size_t)(NP + b * 4 + t) * 512 + c) = o; }
;             for (int r = 0; r < 15; ++r) { const f32x4 v = r < 11 ? *(const f32x4*)(sp + (size_t)(r + 4) * 512) : *(const f32x4*)(up + (size_t)(r - 11) * 512);
;                 *(f32x4*)(p.out + O_POOLS + ((size_t)b * 15 + r) * 512 + c) = v; } }
.LBB0_599:
	s_or_b64 exec, exec, s[22:23]
	v_xor_b32_e32 v3, 0x80000000, v3
	v_xor_b32_e32 v2, 0x80000000, v2
	v_pk_fma_f32 v[2:3], v[22:23], v[26:27], v[2:3]
	v_pk_fma_f32 v[0:1], v[18:19], v[24:25], v[0:1] neg_lo:[0,0,1] neg_hi:[0,0,1]
	v_lshl_add_u64 v[14:15], s[60:61], 0, v[12:13]
	v_cvt_pk_bf16_f32 v0, v0, v1
	v_cvt_pk_bf16_f32 v1, v2, v3
	v_or_b32_e32 v2, 3, v8
	v_lshlrev_b32_e32 v4, 2, v10
	v_ashrrev_i32_e32 v3, 31, v2
	v_lshl_add_u64 v[14:15], v[14:15], 0, v[4:5]
	v_lshlrev_b64 v[2:3], 10, v[2:3]
	v_lshl_add_u64 v[2:3], v[16:17], 0, v[2:3]
	global_store_dwordx2 v[2:3], v[0:1], off
	v_lshl_add_u64 v[16:17], s[4:5], 0, v[4:5]
	v_lshl_add_u64 v[12:13], v[16:17], 0, v[12:13]
	v_add_u32_e32 v140, s80, v140
	v_add_u32_e32 v141, s3, v141
	v_cmp_lt_i32_e32 vcc, s35, v140
	s_or_b64 s[14:15], vcc, s[14:15]
	s_mov_b64 s[6:7], 0x3000
	v_lshl_add_u64 v[32:33], v[14:15], 0, s[6:7]
	s_mov_b64 s[6:7], 0x5000
	v_lshl_add_u64 v[34:35], v[14:15], 0, s[6:7]
	s_mov_b64 s[6:7], 0x7000
	v_lshl_add_u64 v[36:37], v[14:15], 0, s[6:7]
	v_lshl_add_u64 v[38:39], v[6:7], 0, s[20:21]
	global_load_dwordx4 v[40:43], v[32:33], off offset:-4096
	global_load_dwordx4 v[44:47], v[32:33], off offset:-2048
	global_load_dwordx4 v[48:51], v[32:33], off
	global_load_dwordx4 v[52:55], v[32:33], off offset:2048
	global_load_dwordx4 v[56:59], v[34:35], off offset:-4096
	global_load_dwordx4 v[60:63], v[34:35], off offset:-2048
	global_load_dwordx4 v[64:67], v[34:35], off
	global_load_dwordx4 v[68:71], v[34:35], off offset:2048
	global_load_dwordx4 v[72:75], v[36:37], off offset:-4096
	global_load_dwordx4 v[76:79], v[36:37], off offset:-2048
	global_load_dwordx4 v[80:83], v[36:37], off
	global_load_dwordx4 v[84:87], v[6:7], off
	global_load_dwordx4 v[88:91], v[6:7], off offset:2048
	global_load_dwordx4 v[92:95], v[20:21], off
	global_load_dwordx4 v[96:99], v[38:39], off
	s_mov_b64 s[6:7], 0x1000
	v_lshl_add_u64 v[32:33], v[12:13], 0, s[6:7]
	s_mov_b64 s[6:7], 0x3000
	v_lshl_add_u64 v[34:35], v[12:13], 0, s[6:7]
	s_mov_b64 s[6:7], 0x5000
	v_lshl_add_u64 v[36:37], v[12:13], 0, s[6:7]
	s_mov_b64 s[6:7], 0x7000
	v_lshl_add_u64 v[38:39], v[12:13], 0, s[6:7]
	s_waitcnt vmcnt(0)
	global_store_dwordx4 v[32:33], v[40:43], off offset:-4096
	global_store_dwordx4 v[32:33], v[44:47], off offset:-2048
	global_store_dwordx4 v[32:33], v[48:51], off
	global_store_dwordx4 v[32:33], v[52:55], off offset:2048
	global_store_dwordx4 v[34:35], v[56:59], off offset:-4096
	global_store_dwordx4 v[34:35], v[60:63], off offset:-2048
	global_store_dwordx4 v[34:35], v[64:67], off
	global_store_dwordx4 v[34:35], v[68:71], off offset:2048
	global_store_dwordx4 v[36:37], v[72:75], off offset:-4096
	global_store_dwordx4 v[36:37], v[76:79], off offset:-2048
	global_store_dwordx4 v[36:37], v[80:83], off
	global_store_dwordx4 v[36:37], v[84:87], off offset:2048
	global_store_dwordx4 v[38:39], v[88:91], off offset:-4096
	global_store_dwordx4 v[38:39], v[92:95], off offset:-2048
	global_store_dwordx4 v[38:39], v[96:99], off
	s_andn2_b64 exec, exec, s[14:15]
	s_cbranch_execz .LBB0_615
.LBB0_600:
	v_ashrrev_i32_e32 v12, 7, v140
	v_lshl_add_u32 v8, v12, 2, v11
	v_lshlrev_b32_e32 v13, 2, v140
	v_ashrrev_i32_e32 v9, 31, v8
	v_and_b32_e32 v10, 0x1fc, v13
	v_lshlrev_b64 v[0:1], 11, v[8:9]
	v_lshl_add_u64 v[0:1], s[0:1], 0, v[0:1]
	v_lshlrev_b32_e32 v4, 2, v10
	v_lshl_add_u64 v[6:7], v[0:1], 0, v[4:5]
	global_load_dwordx4 v[0:3], v[6:7], off
	v_mul_lo_u32 v12, v12, 15
	v_bfe_u32 v31, v13, 7, 2
	v_ashrrev_i32_e32 v13, 31, v12
	v_lshlrev_b32_e32 v4, 2, v141
	v_lshlrev_b64 v[12:13], 11, v[12:13]
	v_and_or_b32 v14, v4, s26, v12
	v_mov_b32_e32 v15, v13
	v_lshl_add_u64 v[14:15], s[12:13], 0, v[14:15]
	s_mov_b64 s[6:7], 0
	v_lshlrev_b32_e64 v30, v31, 2
	v_mov_b64_e32 v[16:17], v[14:15]
	s_mov_b32 s22, 1
	s_mov_b32 s6, 0xfffff800
	s_mov_b32 s7, -1
	v_lshl_add_u64 v[32:33], v[14:15], 0, s[6:7]
	s_mov_b32 s6, 0xffffd800
	v_lshl_add_u64 v[34:35], v[14:15], 0, s[6:7]
	s_mov_b32 s6, 0xffffb800
	v_lshl_add_u64 v[36:37], v[14:15], 0, s[6:7]
	s_mov_b32 s6, 0xffff9800
	v_lshl_add_u64 v[38:39], v[14:15], 0, s[6:7]
	global_load_dwordx4 v[40:43], v[32:33], off offset:2048
	global_load_dwordx4 v[44:47], v[32:33], off
	global_load_dwordx4 v[48:51], v[32:33], off offset:-2048
	global_load_dwordx4 v[52:55], v[32:33], off offset:-4096
	global_load_dwordx4 v[56:59], v[34:35], off offset:2048
	global_load_dwordx4 v[60:63], v[34:35], off
	global_load_dwordx4 v[64:67], v[34:35], off offset:-2048
	global_load_dwordx4 v[68:71], v[34:35], off offset:-4096
	global_load_dwordx4 v[72:75], v[36:37], off offset:2048
	global_load_dwordx4 v[76:79], v[36:37], off
	global_load_dwordx4 v[80:83], v[36:37], off offset:-2048
	global_load_dwordx4 v[84:87], v[36:37], off offset:-4096
	global_load_dwordx4 v[88:91], v[38:39], off offset:2048
	global_load_dwordx4 v[92:95], v[38:39], off
	global_load_dwordx4 v[96:99], v[38:39], off offset:-2048
	s_mov_b64 s[6:7], 0
	s_waitcnt vmcnt(0)
; __global__ void __launch_bounds__(512, 2) mega(Params p) {
;     ...
;         for (int it = gt; it < 32 * 128; it += NGT) { const int cq = it & 127, b = it >> 7; const int c = cq * 4, gi = c >> 7, w = 2 << gi;
;             const float* sp = p.in[2] + (size_t)b * 15 * 512 + c; const float* up = upool + (size_t)(NP + b * 4) * 512 + c;
;             for (int t = 0; t < 4; ++t) { f32x4 sum = (f32x4){0.f, 0.f, 0.f, 0.f};
;                 for (int s = 0; s < w; ++s) { const int e = 15 + t - s; sum += e >= 15 ? *(const f32x4*)(up + (size_t)(e - 15) * 512) : *(const f32x4*)(sp + (size_t)e * 512); }
;                 const f32x4 uv = *(const f32x4*)(up + (size_t)t * 512); const f32x4 dv = sum * (1.0f / (float)w) - uv;
;                 u32x2 o; o.x = pk2(dv[0], dv[1]); o.y = pk2(dv[2], dv[3]); *(u32x2*)(dbuf + (size_t)(NP + b * 4 + t) * 512 + c) = o; }
	v_pk_add_f32 v[22:23], v[2:3], 0 op_sel_hi:[1,0]
	v_pk_add_f32 v[20:21], v[0:1], 0 op_sel_hi:[1,0]
	v_cmp_lt_u32_e32 vcc, 1, v30
	v_cndmask_b32_e32 v100, 0, v40, vcc
	v_cndmask_b32_e32 v101, 0, v41, vcc
	v_cndmask_b32_e32 v102, 0, v42, vcc
	v_cndmask_b32_e32 v103, 0, v43, vcc
	v_pk_add_f32 v[22:23], v[22:23], v[102:103]
	v_pk_add_f32 v[20:21], v[20:21], v[100:101]
	v_cmp_lt_u32_e32 vcc, 2, v30
	v_cndmask_b32_e32 v100, 0, v44, vcc
	v_cndmask_b32_e32 v101, 0, v45, vcc
	v_cndmask_b32_e32 v102, 0, v46, vcc
	v_cndmask_b32_e32 v103, 0, v47, vcc
	v_pk_add_f32 v[22:23], v[22:23], v[102:103]
	v_pk_add_f32 v[20:21], v[20:21], v[100:101]
	v_cmp_lt_u32_e32 vcc, 3, v30
	v_cndmask_b32_e32 v100, 0, v48, vcc
	v_cndmask_b32_e32 v101, 0, v49, vcc
	v_cndmask_b32_e32 v102, 0, v50, vcc
	v_cndmask_b32_e32 v103, 0, v51, vcc
	v_pk_add_f32 v[22:23], v[22:23], v[102:103]
	v_pk_add_f32 v[20:21], v[20:21], v[100:101]
	v_cmp_lt_u32_e32 vcc, 4, v30
	v_cndmask_b32_e32 v100, 0, v52, vcc
	v_cndmask_b32_e32 v101, 0, v53, vcc
	v_cndmask_b32_e32 v102, 0, v54, vcc
	v_cndmask_b32_e32 v103, 0, v55, vcc
	v_pk_add_f32 v[22:23], v[22:23], v[102:103]
	v_pk_add_f32 v[20:21], v[20:21], v[100:101]
	v_cmp_lt_u32_e32 vcc, 5, v30
	v_cndmask_b32_e32 v100, 0, v56, vcc
	v_cndmask_b32_e32 v101, 0, v57, vcc
	v_cndmask_b32_e32 v102, 0, v58, vcc
	v_cndmask_b32_e32 v103, 0, v59, vcc
	v_pk_add_f32 v[22:23], v[22:23], v[102:103]
	v_pk_add_f32 v[20:21], v[20:21], v[100:101]
	v_cmp_lt_u32_e32 vcc, 6, v30
	v_cndmask_b32_e32 v100, 0, v60, vcc
	v_cndmask_b32_e32 v101, 0, v61, vcc
	v_cndmask_b32_e32 v102, 0, v62, vcc
	v_cndmask_b32_e32 v103, 0, v63, vcc
	v_pk_add_f32 v[22:23], v[22:23], v[102:103]
	v_pk_add_f32 v[20:21], v[20:21], v[100:101]
	v_cmp_lt_u32_e32 vcc, 7, v30
	v_cndmask_b32_e32 v100, 0, v64, vcc
	v_cndmask_b32_e32 v101, 0, v65, vcc
	v_cndmask_b32_e32 v102, 0, v66, vcc
	v_cndmask_b32_e32 v103, 0, v67, vcc
	v_pk_add_f32 v[22:23], v[22:23], v[102:103]
	v_pk_add_f32 v[20:21], v[20:21], v[100:101]
	v_cmp_lt_u32_e32 vcc, 8, v30
	v_cndmask_b32_e32 v100, 0, v68, vcc
	v_cndmask_b32_e32 v101, 0, v69, vcc
	v_cndmask_b32_e32 v102, 0, v70, vcc
	v_cndmask_b32_e32 v103, 0, v71, vcc
	v_pk_add_f32 v[22:23], v[22:23], v[102:103]
	v_pk_add_f32 v[20:21], v[20:21], v[100:101]
	v_cmp_lt_u32_e32 vcc, 9, v30
	v_cndmask_b32_e32 v100, 0, v72, vcc
	v_cndmask_b32_e32 v101, 0, v73, vcc
	v_cndmask_b32_e32 v102, 0, v74, vcc
	v_cndmask_b32_e32 v103, 0, v75, vcc
	v_pk_add_f32 v[22:23], v[22:23], v[102:103]
	v_pk_add_f32 v[20:21], v[20:21], v[100:101]
	v_cmp_lt_u32_e32 vcc, 10, v30
	v_cndmask_b32_e32 v100, 0, v76, vcc
	v_cndmask_b32_e32 v101, 0, v77, vcc
	v_cndmask_b32_e32 v102, 0, v78, vcc
	v_cndmask_b32_e32 v103, 0, v79, vcc
	v_pk_add_f32 v[22:23], v[22:23], v[102:103]
	v_pk_add_f32 v[20:21], v[20:21], v[100:101]
	v_cmp_lt_u32_e32 vcc, 11, v30
	v_cndmask_b32_e32 v100, 0, v80, vcc
	v_cndmask_b32_e32 v101, 0, v81, vcc
	v_cndmask_b32_e32 v102, 0, v82, vcc
	v_cndmask_b32_e32 v103, 0, v83, vcc
	v_pk_add_f32 v[22:23], v[22:23], v[102:103]
	v_pk_add_f32 v[20:21], v[20:21], v[100:101]
	v_cmp_lt_u32_e32 vcc, 12, v30
	v_cndmask_b32_e32 v100, 0, v84, vcc
	v_cndmask_b32_e32 v101, 0, v85, vcc
	v_cndmask_b32_e32 v102, 0, v86, vcc
	v_cndmask_b32_e32 v103, 0, v87, vcc
	v_pk_add_f32 v[22:23], v[22:23], v[102:103]
	v_pk_add_f32 v[20:21], v[20:21], v[100:101]
	v_cmp_lt_u32_e32 vcc, 13, v30
	v_cndmask_b32_e32 v100, 0, v88, vcc
	v_cndmask_b32_e32 v101, 0, v89, vcc
	v_cndmask_b32_e32 v102, 0, v90, vcc
	v_cndmask_b32_e32 v103, 0, v91, vcc
	v_pk_add_f32 v[22:23], v[22:23], v[102:103]
	v_pk_add_f32 v[20:21], v[20:21], v[100:101]
	v_cmp_lt_u32_e32 vcc, 14, v30
	v_cndmask_b32_e32 v100, 0, v92, vcc
	v_cndmask_b32_e32 v101, 0, v93, vcc
	v_cndmask_b32_e32 v102, 0, v94, vcc
	v_cndmask_b32_e32 v103, 0, v95, vcc
	v_pk_add_f32 v[22:23], v[22:23], v[102:103]
	v_pk_add_f32 v[20:21], v[20:21], v[100:101]
	v_cmp_lt_u32_e32 vcc, 15, v30
	v_cndmask_b32_e32 v100, 0, v96, vcc
	v_cndmask_b32_e32 v101, 0, v97, vcc
	v_cndmask_b32_e32 v102, 0, v98, vcc
	v_cndmask_b32_e32 v103, 0, v99, vcc
	v_pk_add_f32 v[22:23], v[22:23], v[102:103]
	v_pk_add_f32 v[20:21], v[20:21], v[100:101]
	v_cvt_f32_ubyte0_e32 v4, v30
	v_div_scale_f32 v16, s[6:7], v4, v4, 1.0
	v_rcp_f32_e32 v17, v16
	v_div_scale_f32 v18, vcc, 1.0, v4, 1.0
	v_xor_b32_e32 v3, 0x80000000, v3
	v_fma_f32 v19, -v16, v17, 1.0
	v_fmac_f32_e32 v17, v19, v17
	v_mul_f32_e32 v19, v18, v17
	v_fma_f32 v24, -v16, v19, v18
	v_fmac_f32_e32 v19, v24, v17
	v_fma_f32 v16, -v16, v19, v18
	v_div_fmas_f32 v16, v16, v17, v19
	v_div_fixup_f32 v18, v16, v4, 1.0
	v_xor_b32_e32 v2, 0x80000000, v2
	v_lshlrev_b32_e32 v4, 1, v10
	v_pk_fma_f32 v[2:3], v[18:19], v[22:23], v[2:3] op_sel_hi:[0,1,1]
	v_pk_fma_f32 v[0:1], v[18:19], v[20:21], v[0:1] op_sel_hi:[0,1,1] neg_lo:[0,0,1] neg_hi:[0,0,1]
	v_lshl_add_u64 v[16:17], s[10:11], 0, v[4:5]
	v_cvt_pk_bf16_f32 v0, v0, v1
	v_cvt_pk_bf16_f32 v1, v2, v3
	v_lshlrev_b64 v[2:3], 10, v[8:9]
	v_lshl_add_u64 v[2:3], v[16:17], 0, v[2:3]
	global_store_dwordx2 v[2:3], v[0:1], off
	global_load_dwordx4 v[0:3], v[6:7], off offset:2048
	s_nop 0
	global_load_dwordx4 v[20:23], v[6:7], off
	v_cmp_lt_u32_e64 s[6:7], s27, v10
	s_waitcnt vmcnt(1)
	v_pk_add_f32 v[24:25], v[2:3], 0 op_sel_hi:[1,0]
	v_pk_add_f32 v[26:27], v[0:1], 0 op_sel_hi:[1,0]
	s_waitcnt vmcnt(0)
	v_pk_add_f32 v[22:23], v[24:25], v[22:23]
	v_pk_add_f32 v[20:21], v[26:27], v[20:21]
	s_and_saveexec_b64 s[22:23], s[6:7]
	s_cbranch_execz .LBB0_606
; __global__ void __launch_bounds__(512, 2) mega(Params p) {
;     ...
;             for (int t = 0; t < 4; ++t) { f32x4 sum = (f32x4){0.f, 0.f, 0.f, 0.f};
;                 for (int s = 0; s < w; ++s) { const int e = 15 + t - s; sum += e >= 15 ? *(const f32x4*)(up + (size_t)(e - 15) * 512) : *(const f32x4*)(sp + (size_t)e * 512); }
;                 const f32x4 uv = *(const f32x4*)(up + (size_t)t * 512); const f32x4 dv = sum * (1.0f / (float)w) - uv;
;                 u32x2 o; o.x = pk2(dv[0], dv[1]); o.y = pk2(dv[2], dv[3]); *(u32x2*)(dbuf + (size_t)(NP + b * 4 + t) * 512 + c) = o; }
	v_add_u32_e32 v4, -2, v30
	s_mov_b64 s[24:25], 0
	v_mov_b64_e32 v[24:25], v[14:15]
	v_cmp_lt_u32_e32 vcc, 2, v30
	v_cndmask_b32_e32 v100, 0, v40, vcc
	v_cndmask_b32_e32 v101, 0, v41, vcc
	v_cndmask_b32_e32 v102, 0, v42, vcc
	v_cndmask_b32_e32 v103, 0, v43, vcc
	v_pk_add_f32 v[22:23], v[22:23], v[102:103]
	v_pk_add_f32 v[20:21], v[20:21], v[100:101]
	v_cmp_lt_u32_e32 vcc, 3, v30
	v_cndmask_b32_e32 v100, 0, v44, vcc
	v_cndmask_b32_e32 v101, 0, v45, vcc
	v_cndmask_b32_e32 v102, 0, v46, vcc
	v_cndmask_b32_e32 v103, 0, v47, vcc
	v_pk_add_f32 v[22:23], v[22:23], v[102:103]
	v_pk_add_f32 v[20:21], v[20:21], v[100:101]
	v_cmp_lt_u32_e32 vcc, 4, v30
	v_cndmask_b32_e32 v100, 0, v48, vcc
	v_cndmask_b32_e32 v101, 0, v49, vcc
	v_cndmask_b32_e32 v102, 0, v50, vcc
	v_cndmask_b32_e32 v103, 0, v51, vcc
	v_pk_add_f32 v[22:23], v[22:23], v[102:103]
	v_pk_add_f32 v[20:21], v[20:21], v[100:101]
	v_cmp_lt_u32_e32 vcc, 5, v30
	v_cndmask_b32_e32 v100, 0, v52, vcc
	v_cndmask_b32_e32 v101, 0, v53, vcc
	v_cndmask_b32_e32 v102, 0, v54, vcc
	v_cndmask_b32_e32 v103, 0, v55, vcc
	v_pk_add_f32 v[22:23], v[22:23], v[102:103]
	v_pk_add_f32 v[20:21], v[20:21], v[100:101]
	v_cmp_lt_u32_e32 vcc, 6, v30
	v_cndmask_b32_e32 v100, 0, v56, vcc
	v_cndmask_b32_e32 v101, 0, v57, vcc
	v_cndmask_b32_e32 v102, 0, v58, vcc
	v_cndmask_b32_e32 v103, 0, v59, vcc
	v_pk_add_f32 v[22:23], v[22:23], v[102:103]
	v_pk_add_f32 v[20:21], v[20:21], v[100:101]
	v_cmp_lt_u32_e32 vcc, 7, v30
	v_cndmask_b32_e32 v100, 0, v60, vcc
	v_cndmask_b32_e32 v101, 0, v61, vcc
	v_cndmask_b32_e32 v102, 0, v62, vcc
	v_cndmask_b32_e32 v103, 0, v63, vcc
	v_pk_add_f32 v[22:23], v[22:23], v[102:103]
	v_pk_add_f32 v[20:21], v[20:21], v[100:101]
	v_cmp_lt_u32_e32 vcc, 8, v30
	v_cndmask_b32_e32 v100, 0, v64, vcc
	v_cndmask_b32_e32 v101, 0, v65, vcc
	v_cndmask_b32_e32 v102, 0, v66, vcc
	v_cndmask_b32_e32 v103, 0, v67, vcc
	v_pk_add_f32 v[22:23], v[22:23], v[102:103]
	v_pk_add_f32 v[20:21], v[20:21], v[100:101]
	v_cmp_lt_u32_e32 vcc, 9, v30
	v_cndmask_b32_e32 v100, 0, v68, vcc
	v_cndmask_b32_e32 v101, 0, v69, vcc
	v_cndmask_b32_e32 v102, 0, v70, vcc
	v_cndmask_b32_e32 v103, 0, v71, vcc
	v_pk_add_f32 v[22:23], v[22:23], v[102:103]
	v_pk_add_f32 v[20:21], v[20:21], v[100:101]
	v_cmp_lt_u32_e32 vcc, 10, v30
	v_cndmask_b32_e32 v100, 0, v72, vcc
	v_cndmask_b32_e32 v101, 0, v73, vcc
	v_cndmask_b32_e32 v102, 0, v74, vcc
	v_cndmask_b32_e32 v103, 0, v75, vcc
	v_pk_add_f32 v[22:23], v[22:23], v[102:103]
	v_pk_add_f32 v[20:21], v[20:21], v[100:101]
	v_cmp_lt_u32_e32 vcc, 11, v30
	v_cndmask_b32_e32 v100, 0, v76, vcc
	v_cndmask_b32_e32 v101, 0, v77, vcc
	v_cndmask_b32_e32 v102, 0, v78, vcc
	v_cndmask_b32_e32 v103, 0, v79, vcc
	v_pk_add_f32 v[22:23], v[22:23], v[102:103]
	v_pk_add_f32 v[20:21], v[20:21], v[100:101]
	v_cmp_lt_u32_e32 vcc, 12, v30
	v_cndmask_b32_e32 v100, 0, v80, vcc
	v_cndmask_b32_e32 v101, 0, v81, vcc
	v_cndmask_b32_e32 v102, 0, v82, vcc
	v_cndmask_b32_e32 v103, 0, v83, vcc
	v_pk_add_f32 v[22:23], v[22:23], v[102:103]
	v_pk_add_f32 v[20:21], v[20:21], v[100:101]
	v_cmp_lt_u32_e32 vcc, 13, v30
	v_cndmask_b32_e32 v100, 0, v84, vcc
	v_cndmask_b32_e32 v101, 0, v85, vcc
	v_cndmask_b32_e32 v102, 0, v86, vcc
	v_cndmask_b32_e32 v103, 0, v87, vcc
	v_pk_add_f32 v[22:23], v[22:23], v[102:103]
	v_pk_add_f32 v[20:21], v[20:21], v[100:101]
	v_cmp_lt_u32_e32 vcc, 14, v30
	v_cndmask_b32_e32 v100, 0, v88, vcc
	v_cndmask_b32_e32 v101, 0, v89, vcc
	v_cndmask_b32_e32 v102, 0, v90, vcc
	v_cndmask_b32_e32 v103, 0, v91, vcc
	v_pk_add_f32 v[22:23], v[22:23], v[102:103]
	v_pk_add_f32 v[20:21], v[20:21], v[100:101]
	v_cmp_lt_u32_e32 vcc, 15, v30
	v_cndmask_b32_e32 v100, 0, v92, vcc
	v_cndmask_b32_e32 v101, 0, v93, vcc
	v_cndmask_b32_e32 v102, 0, v94, vcc
	v_cndmask_b32_e32 v103, 0, v95, vcc
	v_pk_add_f32 v[22:23], v[22:23], v[102:103]
	v_pk_add_f32 v[20:21], v[20:21], v[100:101]
.LBB0_606:
	s_or_b64 exec, exec, s[22:23]
	v_mov_b32_e32 v19, v18
	v_xor_b32_e32 v3, 0x80000000, v3
	v_xor_b32_e32 v2, 0x80000000, v2
	v_mov_b32_e32 v24, v18
	v_mov_b32_e32 v25, v18
	v_pk_fma_f32 v[2:3], v[24:25], v[22:23], v[2:3]
	v_pk_fma_f32 v[0:1], v[18:19], v[20:21], v[0:1] neg_lo:[0,0,1] neg_hi:[0,0,1]
	v_add_co_u32_e32 v24, vcc, s2, v6
	v_cvt_pk_bf16_f32 v0, v0, v1
	v_cvt_pk_bf16_f32 v1, v2, v3
	v_or_b32_e32 v2, 1, v8
	v_ashrrev_i32_e32 v3, 31, v2
	v_lshlrev_b64 v[2:3], 10, v[2:3]
	v_lshl_add_u64 v[2:3], v[16:17], 0, v[2:3]
	global_store_dwordx2 v[2:3], v[0:1], off
	v_addc_co_u32_e32 v25, vcc, 0, v7, vcc
	global_load_dwordx4 v[0:3], v[24:25], off
	global_load_dwordx4 v[20:23], v[6:7], off offset:2048
	s_waitcnt vmcnt(1)
	v_pk_add_f32 v[26:27], v[2:3], 0 op_sel_hi:[1,0]
	v_pk_add_f32 v[28:29], v[0:1], 0 op_sel_hi:[1,0]
	s_waitcnt vmcnt(0)
	v_pk_add_f32 v[26:27], v[26:27], v[22:23]
	v_pk_add_f32 v[28:29], v[28:29], v[20:21]
	s_and_saveexec_b64 s[22:23], s[6:7]
	s_cbranch_execz .LBB0_610
; __global__ void __launch_bounds__(512, 2) mega(Params p) {
;     ...
;             for (int t = 0; t < 4; ++t) { f32x4 sum = (f32x4){0.f, 0.f, 0.f, 0.f};
;                 for (int s = 0; s < w; ++s) { const int e = 15 + t - s; sum += e >= 15 ? *(const f32x4*)(up + (size_t)(e - 15) * 512) : *(const f32x4*)(sp + (size_t)e * 512); }
;                 const f32x4 uv = *(const f32x4*)(up + (size_t)t * 512); const f32x4 dv = sum * (1.0f / (float)w) - uv;
	global_load_dwordx4 v[20:23], v[6:7], off
	v_add_u32_e32 v4, -3, v30
	s_mov_b64 s[24:25], 0
	s_waitcnt vmcnt(0)
	v_pk_add_f32 v[26:27], v[26:27], v[22:23]
	v_pk_add_f32 v[28:29], v[28:29], v[20:21]
	v_mov_b64_e32 v[20:21], v[14:15]
	v_cmp_lt_u32_e32 vcc, 3, v30
	v_cndmask_b32_e32 v100, 0, v40, vcc
	v_cndmask_b32_e32 v101, 0, v41, vcc
	v_cndmask_b32_e32 v102, 0, v42, vcc
	v_cndmask_b32_e32 v103, 0, v43, vcc
	v_pk_add_f32 v[26:27], v[26:27], v[102:103]
	v_pk_add_f32 v[28:29], v[28:29], v[100:101]
	v_cmp_lt_u32_e32 vcc, 4, v30
	v_cndmask_b32_e32 v100, 0, v44, vcc
	v_cndmask_b32_e32 v101, 0, v45, vcc
	v_cndmask_b32_e32 v102, 0, v46, vcc
	v_cndmask_b32_e32 v103, 0, v47, vcc
	v_pk_add_f32 v[26:27], v[26:27], v[102:103]
	v_pk_add_f32 v[28:29], v[28:29], v[100:101]
	v_cmp_lt_u32_e32 vcc, 5, v30
	v_cndmask_b32_e32 v100, 0, v48, vcc
	v_cndmask_b32_e32 v101, 0, v49, vcc
	v_cndmask_b32_e32 v102, 0, v50, vcc
	v_cndmask_b32_e32 v103, 0, v51, vcc
	v_pk_add_f32 v[26:27], v[26:27], v[102:103]
	v_pk_add_f32 v[28:29], v[28:29], v[100:101]
	v_cmp_lt_u32_e32 vcc, 6, v30
	v_cndmask_b32_e32 v100, 0, v52, vcc
	v_cndmask_b32_e32 v101, 0, v53, vcc
	v_cndmask_b32_e32 v102, 0, v54, vcc
	v_cndmask_b32_e32 v103, 0, v55, vcc
	v_pk_add_f32 v[26:27], v[26:27], v[102:103]
	v_pk_add_f32 v[28:29], v[28:29], v[100:101]
	v_cmp_lt_u32_e32 vcc, 7, v30
	v_cndmask_b32_e32 v100, 0, v56, vcc
	v_cndmask_b32_e32 v101, 0, v57, vcc
	v_cndmask_b32_e32 v102, 0, v58, vcc
	v_cndmask_b32_e32 v103, 0, v59, vcc
	v_pk_add_f32 v[26:27], v[26:27], v[102:103]
	v_pk_add_f32 v[28:29], v[28:29], v[100:101]
	v_cmp_lt_u32_e32 vcc, 8, v30
	v_cndmask_b32_e32 v100, 0, v60, vcc
	v_cndmask_b32_e32 v101, 0, v61, vcc
	v_cndmask_b32_e32 v102, 0, v62, vcc
	v_cndmask_b32_e32 v103, 0, v63, vcc
	v_pk_add_f32 v[26:27], v[26:27], v[102:103]
	v_pk_add_f32 v[28:29], v[28:29], v[100:101]
	v_cmp_lt_u32_e32 vcc, 9, v30
	v_cndmask_b32_e32 v100, 0, v64, vcc
	v_cndmask_b32_e32 v101, 0, v65, vcc
	v_cndmask_b32_e32 v102, 0, v66, vcc
	v_cndmask_b32_e32 v103, 0, v67, vcc
	v_pk_add_f32 v[26:27], v[26:27], v[102:103]
	v_pk_add_f32 v[28:29], v[28:29], v[100:101]
	v_cmp_lt_u32_e32 vcc, 10, v30
	v_cndmask_b32_e32 v100, 0, v68, vcc
	v_cndmask_b32_e32 v101, 0, v69, vcc
	v_cndmask_b32_e32 v102, 0, v70, vcc
	v_cndmask_b32_e32 v103, 0, v71, vcc
	v_pk_add_f32 v[26:27], v[26:27], v[102:103]
	v_pk_add_f32 v[28:29], v[28:29], v[100:101]
	v_cmp_lt_u32_e32 vcc, 11, v30
	v_cndmask_b32_e32 v100, 0, v72, vcc
	v_cndmask_b32_e32 v101, 0, v73, vcc
	v_cndmask_b32_e32 v102, 0, v74, vcc
	v_cndmask_b32_e32 v103, 0, v75, vcc
	v_pk_add_f32 v[26:27], v[26:27], v[102:103]
	v_pk_add_f32 v[28:29], v[28:29], v[100:101]
	v_cmp_lt_u32_e32 vcc, 12, v30
	v_cndmask_b32_e32 v100, 0, v76, vcc
	v_cndmask_b32_e32 v101, 0, v77, vcc
	v_cndmask_b32_e32 v102, 0, v78, vcc
	v_cndmask_b32_e32 v103, 0, v79, vcc
	v_pk_add_f32 v[26:27], v[26:27], v[102:103]
	v_pk_add_f32 v[28:29], v[28:29], v[100:101]
	v_cmp_lt_u32_e32 vcc, 13, v30
	v_cndmask_b32_e32 v100, 0, v80, vcc
	v_cndmask_b32_e32 v101, 0, v81, vcc
	v_cndmask_b32_e32 v102, 0, v82, vcc
	v_cndmask_b32_e32 v103, 0, v83, vcc
	v_pk_add_f32 v[26:27], v[26:27], v[102:103]
	v_pk_add_f32 v[28:29], v[28:29], v[100:101]
	v_cmp_lt_u32_e32 vcc, 14, v30
	v_cndmask_b32_e32 v100, 0, v84, vcc
	v_cndmask_b32_e32 v101, 0, v85, vcc
	v_cndmask_b32_e32 v102, 0, v86, vcc
	v_cndmask_b32_e32 v103, 0, v87, vcc
	v_pk_add_f32 v[26:27], v[26:27], v[102:103]
	v_pk_add_f32 v[28:29], v[28:29], v[100:101]
	v_cmp_lt_u32_e32 vcc, 15, v30
	v_cndmask_b32_e32 v100, 0, v88, vcc
	v_cndmask_b32_e32 v101, 0, v89, vcc
	v_cndmask_b32_e32 v102, 0, v90, vcc
	v_cndmask_b32_e32 v103, 0, v91, vcc
	v_pk_add_f32 v[26:27], v[26:27], v[102:103]
	v_pk_add_f32 v[28:29], v[28:29], v[100:101]
; __global__ void __launch_bounds__(512, 2) mega(Params p) {
;     ...
;             for (int t = 0; t < 4; ++t) { f32x4 sum = (f32x4){0.f, 0.f, 0.f, 0.f};
;                 for (int s = 0; s < w; ++s) { const int e = 15 + t - s; sum += e >= 15 ? *(const f32x4*)(up + (size_t)(e - 15) * 512) : *(const f32x4*)(sp + (size_t)e * 512); }
;                 const f32x4 uv = *(const f32x4*)(up + (size_t)t * 512); const f32x4 dv = sum * (1.0f / (float)w) - uv;
;                 u32x2 o; o.x = pk2(dv[0], dv[1]); o.y = pk2(dv[2], dv[3]); *(u32x2*)(dbuf + (size_t)(NP + b * 4 + t) * 512 + c) = o; }
.LBB0_610:
	s_or_b64 exec, exec, s[22:23]
	v_xor_b32_e32 v3, 0x80000000, v3
	v_xor_b32_e32 v2, 0x80000000, v2
	v_mov_b32_e32 v22, v18
	v_mov_b32_e32 v23, v18
	v_pk_fma_f32 v[2:3], v[22:23], v[26:27], v[2:3]
	v_pk_fma_f32 v[0:1], v[18:19], v[28:29], v[0:1] neg_lo:[0,0,1] neg_hi:[0,0,1]
	v_lshl_add_u64 v[20:21], v[6:7], 0, s[18:19]
	v_cvt_pk_bf16_f32 v0, v0, v1
	v_cvt_pk_bf16_f32 v1, v2, v3
	v_or_b32_e32 v2, 2, v8
	v_ashrrev_i32_e32 v3, 31, v2
	v_lshlrev_b64 v[2:3], 10, v[2:3]
	v_lshl_add_u64 v[2:3], v[16:17], 0, v[2:3]
	global_store_dwordx2 v[2:3], v[0:1], off
	global_load_dwordx4 v[0:3], v[24:25], off offset:2048
	s_nop 0
	global_load_dwordx4 v[24:27], v[20:21], off
	s_waitcnt vmcnt(1)
	v_pk_add_f32 v[28:29], v[2:3], 0 op_sel_hi:[1,0]
	v_pk_add_f32 v[32:33], v[0:1], 0 op_sel_hi:[1,0]
	s_waitcnt vmcnt(0)
	v_pk_add_f32 v[26:27], v[28:29], v[26:27]
	v_pk_add_f32 v[24:25], v[32:33], v[24:25]
	s_and_saveexec_b64 s[22:23], s[6:7]
	s_cbranch_execz .LBB0_599
	global_load_dwordx4 v[32:35], v[6:7], off offset:2048
	global_load_dwordx4 v[36:39], v[6:7], off
	v_cmp_ne_u32_e32 vcc, 1, v31
	s_waitcnt vmcnt(1)
	v_pk_add_f32 v[26:27], v[26:27], v[34:35]
	v_pk_add_f32 v[24:25], v[24:25], v[32:33]
	s_waitcnt vmcnt(0)
	v_pk_add_f32 v[26:27], v[26:27], v[38:39]
	v_pk_add_f32 v[24:25], v[24:25], v[36:37]
	s_and_saveexec_b64 s[6:7], vcc
	s_cbranch_execz .LBB0_598
	v_add_u32_e32 v4, -4, v30
	s_mov_b64 s[24:25], 0
	v_cmp_lt_u32_e32 vcc, 4, v30
	v_cndmask_b32_e32 v100, 0, v40, vcc
	v_cndmask_b32_e32 v101, 0, v41, vcc
	v_cndmask_b32_e32 v102, 0, v42, vcc
	v_cndmask_b32_e32 v103, 0, v43, vcc
	v_pk_add_f32 v[26:27], v[26:27], v[102:103]
	v_pk_add_f32 v[24:25], v[24:25], v[100:101]
	v_cmp_lt_u32_e32 vcc, 5, v30
	v_cndmask_b32_e32 v100, 0, v44, vcc
	v_cndmask_b32_e32 v101, 0, v45, vcc
	v_cndmask_b32_e32 v102, 0, v46, vcc
	v_cndmask_b32_e32 v103, 0, v47, vcc
	v_pk_add_f32 v[26:27], v[26:27], v[102:103]
	v_pk_add_f32 v[24:25], v[24:25], v[100:101]
	v_cmp_lt_u32_e32 vcc, 6, v30
	v_cndmask_b32_e32 v100, 0, v48, vcc
	v_cndmask_b32_e32 v101, 0, v49, vcc
	v_cndmask_b32_e32 v102, 0, v50, vcc
	v_cndmask_b32_e32 v103, 0, v51, vcc
	v_pk_add_f32 v[26:27], v[26:27], v[102:103]
	v_pk_add_f32 v[24:25], v[24:25], v[100:101]
	v_cmp_lt_u32_e32 vcc, 7, v30
	v_cndmask_b32_e32 v100, 0, v52, vcc
	v_cndmask_b32_e32 v101, 0, v53, vcc
	v_cndmask_b32_e32 v102, 0, v54, vcc
	v_cndmask_b32_e32 v103, 0, v55, vcc
	v_pk_add_f32 v[26:27], v[26:27], v[102:103]
	v_pk_add_f32 v[24:25], v[24:25], v[100:101]
	v_cmp_lt_u32_e32 vcc, 8, v30
	v_cndmask_b32_e32 v100, 0, v56, vcc
	v_cndmask_b32_e32 v101, 0, v57, vcc
	v_cndmask_b32_e32 v102, 0, v58, vcc
	v_cndmask_b32_e32 v103, 0, v59, vcc
	v_pk_add_f32 v[26:27], v[26:27], v[102:103]
	v_pk_add_f32 v[24:25], v[24:25], v[100:101]
	v_cmp_lt_u32_e32 vcc, 9, v30
	v_cndmask_b32_e32 v100, 0, v60, vcc
	v_cndmask_b32_e32 v101, 0, v61, vcc
	v_cndmask_b32_e32 v102, 0, v62, vcc
	v_cndmask_b32_e32 v103, 0, v63, vcc
	v_pk_add_f32 v[26:27], v[26:27], v[102:103]
	v_pk_add_f32 v[24:25], v[24:25], v[100:101]
	v_cmp_lt_u32_e32 vcc, 10, v30
	v_cndmask_b32_e32 v100, 0, v64, vcc
	v_cndmask_b32_e32 v101, 0, v65, vcc
	v_cndmask_b32_e32 v102, 0, v66, vcc
	v_cndmask_b32_e32 v103, 0, v67, vcc
	v_pk_add_f32 v[26:27], v[26:27], v[102:103]
	v_pk_add_f32 v[24:25], v[24:25], v[100:101]
	v_cmp_lt_u32_e32 vcc, 11, v30
	v_cndmask_b32_e32 v100, 0, v68, vcc
	v_cndmask_b32_e32 v101, 0, v69, vcc
	v_cndmask_b32_e32 v102, 0, v70, vcc
	v_cndmask_b32_e32 v103, 0, v71, vcc
	v_pk_add_f32 v[26:27], v[26:27], v[102:103]
	v_pk_add_f32 v[24:25], v[24:25], v[100:101]
	v_cmp_lt_u32_e32 vcc, 12, v30
	v_cndmask_b32_e32 v100, 0, v72, vcc
	v_cndmask_b32_e32 v101, 0, v73, vcc
	v_cndmask_b32_e32 v102, 0, v74, vcc
	v_cndmask_b32_e32 v103, 0, v75, vcc
	v_pk_add_f32 v[26:27], v[26:27], v[102:103]
	v_pk_add_f32 v[24:25], v[24:25], v[100:101]
	v_cmp_lt_u32_e32 vcc, 13, v30
	v_cndmask_b32_e32 v100, 0, v76, vcc
	v_cndmask_b32_e32 v101, 0, v77, vcc
	v_cndmask_b32_e32 v102, 0, v78, vcc
	v_cndmask_b32_e32 v103, 0, v79, vcc
	v_pk_add_f32 v[26:27], v[26:27], v[102:103]
	v_pk_add_f32 v[24:25], v[24:25], v[100:101]
	v_cmp_lt_u32_e32 vcc, 14, v30
	v_cndmask_b32_e32 v100, 0, v80, vcc
	v_cndmask_b32_e32 v101, 0, v81, vcc
	v_cndmask_b32_e32 v102, 0, v82, vcc
	v_cndmask_b32_e32 v103, 0, v83, vcc
	v_pk_add_f32 v[26:27], v[26:27], v[102:103]
	v_pk_add_f32 v[24:25], v[24:25], v[100:101]
	v_cmp_lt_u32_e32 vcc, 15, v30
	v_cndmask_b32_e32 v100, 0, v84, vcc
	v_cndmask_b32_e32 v101, 0, v85, vcc
	v_cndmask_b32_e32 v102, 0, v86, vcc
	v_cndmask_b32_e32 v103, 0, v87, vcc
	v_pk_add_f32 v[26:27], v[26:27], v[102:103]
	v_pk_add_f32 v[24:25], v[24:25], v[100:101]
	s_branch .LBB0_598
